# read-once sources (short conv inputs, x, projection weight conversion inputs) loaded with non-temporal loads
# speedup vs baseline: 1.0478x; 1.0135x over previous
; __device__ __forceinline__ int fresh_tid() { int t = threadIdx.x; asm volatile("" : "+v"(t)); return t; }
; __device__ void conv_naive(const Params& p, int l, const bf16_t* proj, bf16_t* ycat) {
;     for (int gidx = blockIdx.x * NTHREADS + fresh_tid(); gidx < (SEQ / 8) * 128; gidx += gridDim.x * NTHREADS) {
;         const int tb = (gidx >> 7) * 8, c = (gidx & 127) * 4;
;         u32x2 hh[10], cc[10], bb[8];
; #pragma unroll
;         for (int j = 0; j < 10; ++j) { const int ts = tb + j - 1; const bool ok = ts >= 0 && ts < SEQ; const int tc = ok ? ts : tb;
;             hh[j] = *(const u32x2*)(proj + (size_t)tc * NP + CH + c); cc[j] = *(const u32x2*)(proj + (size_t)tc * NP + CC + c);
;             if (!ok) { hh[j].x = 0u; hh[j].y = 0u; } }
; #pragma unroll
;         for (int j = 0; j < 8; ++j) bb[j] = *(const u32x2*)(proj + (size_t)(tb + j) * NP + CB + c);
.LBB0_482:
	v_ashrrev_i32_e32 v52, 4, v54
	v_and_b32_e32 v0, -8, v52
	v_add_u32_e32 v1, -1, v0
	v_cmp_gt_u32_e64 s[4:5], s22, v1
	v_and_b32_e32 v53, 0x1fc, v55
	v_mov_b64_e32 v[14:15], s[94:95]
	v_cndmask_b32_e64 v1, v0, v1, s[4:5]
	v_mad_i64_i32 v[2:3], s[12:13], v1, s63, v[14:15]
	v_lshlrev_b32_e32 v188, 1, v53
	v_lshl_add_u64 v[2:3], v[2:3], 0, v[188:189]
	v_add_co_u32_e32 v4, vcc, 0x1000, v2
	v_or_b32_e32 v10, 2, v0
	s_nop 0
	v_addc_co_u32_e32 v5, vcc, 0, v3, vcc
	global_load_dwordx2 v[120:121], v[4:5], off offset:3584 nt
	v_add_co_u32_e32 v2, vcc, 0x2000, v2
	v_or_b32_e32 v8, 3, v0
	s_nop 0
	v_addc_co_u32_e32 v3, vcc, 0, v3, vcc
	global_load_dwordx2 v[24:25], v[2:3], off offset:1536 nt
	v_mad_i64_i32 v[2:3], s[12:13], v0, s63, v[14:15]
	v_lshl_add_u64 v[2:3], v[2:3], 0, v[188:189]
	v_or_b32_e32 v6, 4, v0
	v_or_b32_e32 v28, 1, v0
	v_ashrrev_i32_e32 v1, 31, v0
	v_ashrrev_i32_e32 v29, 31, v28
	v_ashrrev_i32_e32 v11, 31, v10
	v_ashrrev_i32_e32 v9, 31, v8
	v_ashrrev_i32_e32 v7, 31, v6
	v_add_u32_e32 v54, s18, v54
	v_add_u32_e32 v55, s19, v55
	v_cndmask_b32_e64 v140, 0, 1, s[4:5]
	v_add_co_u32_e32 v4, vcc, s66, v2
	s_nop 0
	v_addc_co_u32_e32 v5, vcc, 0, v3, vcc
	global_load_dwordx2 v[122:123], v[4:5], off offset:3584 nt
	v_cmp_gt_u32_e64 s[4:5], s22, v52
	v_add_co_u32_e32 v12, vcc, s92, v2
	s_nop 0
	v_cndmask_b32_e64 v2, 0, 1, s[4:5]
	v_cndmask_b32_e64 v141, 0, 1, s[4:5]
	v_or_b32_e32 v2, v0, v2
	v_addc_co_u32_e32 v13, vcc, 0, v3, vcc
	v_mad_i64_i32 v[2:3], s[12:13], v2, s63, v[14:15]
	v_lshl_add_u64 v[2:3], v[2:3], 0, v[188:189]
	global_load_dwordx2 v[30:31], v[12:13], off offset:1536 nt
	global_load_dwordx2 v[44:45], v[12:13], off offset:512 nt
	v_add_co_u32_e32 v4, vcc, s66, v2
	s_nop 0
	v_addc_co_u32_e32 v5, vcc, 0, v3, vcc
	global_load_dwordx2 v[124:125], v[4:5], off offset:3584 nt
	v_add_co_u32_e32 v2, vcc, s92, v2
	s_nop 0
	v_addc_co_u32_e32 v3, vcc, 0, v3, vcc
	global_load_dwordx2 v[32:33], v[2:3], off offset:1536 nt
	v_cndmask_b32_e64 v2, v0, v10, s[4:5]
	v_mad_i64_i32 v[2:3], s[12:13], v2, s63, v[14:15]
	v_lshl_add_u64 v[2:3], v[2:3], 0, v[188:189]
	v_add_co_u32_e32 v4, vcc, s66, v2
	s_nop 0
	v_addc_co_u32_e32 v5, vcc, 0, v3, vcc
	global_load_dwordx2 v[126:127], v[4:5], off offset:3584 nt
	v_add_co_u32_e32 v2, vcc, s92, v2
	s_nop 1
	v_addc_co_u32_e32 v3, vcc, 0, v3, vcc
	global_load_dwordx2 v[34:35], v[2:3], off offset:1536 nt
	v_cndmask_b32_e64 v2, v0, v8, s[4:5]
	v_mad_i64_i32 v[2:3], s[12:13], v2, s63, v[14:15]
	v_lshl_add_u64 v[2:3], v[2:3], 0, v[188:189]
	v_add_co_u32_e32 v4, vcc, s66, v2
	s_nop 0
	v_addc_co_u32_e32 v5, vcc, 0, v3, vcc
	global_load_dwordx2 v[128:129], v[4:5], off offset:3584 nt
	v_add_co_u32_e32 v2, vcc, s92, v2
	s_nop 1
	v_addc_co_u32_e32 v3, vcc, 0, v3, vcc
	global_load_dwordx2 v[38:39], v[2:3], off offset:1536 nt
	v_cndmask_b32_e64 v2, v0, v6, s[4:5]
	v_mad_i64_i32 v[2:3], s[12:13], v2, s63, v[14:15]
	v_lshl_add_u64 v[2:3], v[2:3], 0, v[188:189]
	v_add_co_u32_e32 v4, vcc, s66, v2
	s_nop 0
	v_addc_co_u32_e32 v5, vcc, 0, v3, vcc
	global_load_dwordx2 v[130:131], v[4:5], off offset:3584 nt
	v_add_co_u32_e32 v2, vcc, s92, v2
	s_nop 1
	v_addc_co_u32_e32 v3, vcc, 0, v3, vcc
	global_load_dwordx2 v[40:41], v[2:3], off offset:1536 nt
	v_or_b32_e32 v4, 5, v0
	v_cndmask_b32_e64 v2, v0, v4, s[4:5]
	v_mad_i64_i32 v[2:3], s[12:13], v2, s63, v[14:15]
	v_lshl_add_u64 v[2:3], v[2:3], 0, v[188:189]
	v_add_co_u32_e32 v16, vcc, s66, v2
	s_nop 0
	v_addc_co_u32_e32 v17, vcc, 0, v3, vcc
	global_load_dwordx2 v[132:133], v[16:17], off offset:3584 nt
	v_add_co_u32_e32 v2, vcc, s92, v2
	v_ashrrev_i32_e32 v5, 31, v4
	s_nop 0
	v_addc_co_u32_e32 v3, vcc, 0, v3, vcc
	global_load_dwordx2 v[42:43], v[2:3], off offset:1536 nt
	v_or_b32_e32 v2, 6, v0
	v_cndmask_b32_e64 v3, v0, v2, s[4:5]
	v_mad_i64_i32 v[16:17], s[12:13], v3, s63, v[14:15]
	v_lshl_add_u64 v[16:17], v[16:17], 0, v[188:189]
	v_add_co_u32_e32 v18, vcc, s66, v16
	v_cndmask_b32_e64 v3, 0, 7, s[4:5]
	s_nop 0
	v_addc_co_u32_e32 v19, vcc, 0, v17, vcc
	global_load_dwordx2 v[134:135], v[18:19], off offset:3584 nt
	v_add_co_u32_e32 v16, vcc, s92, v16
	v_or_b32_e32 v3, v3, v0
	s_nop 0
	v_addc_co_u32_e32 v17, vcc, 0, v17, vcc
	global_load_dwordx2 v[46:47], v[16:17], off offset:1536 nt
	v_mad_i64_i32 v[16:17], s[12:13], v3, s63, v[14:15]
	v_lshl_add_u64 v[16:17], v[16:17], 0, v[188:189]
	v_add_u32_e32 v3, 8, v0
	v_add_co_u32_e32 v18, vcc, s66, v16
	s_nop 0
	v_addc_co_u32_e32 v19, vcc, 0, v17, vcc
	global_load_dwordx2 v[136:137], v[18:19], off offset:3584 nt
	v_add_co_u32_e32 v16, vcc, s92, v16
	s_nop 1
	v_addc_co_u32_e32 v17, vcc, 0, v17, vcc
	global_load_dwordx2 v[48:49], v[16:17], off offset:1536 nt
	v_cmp_gt_u32_e64 s[4:5], s22, v3
	s_nop 1
	v_cndmask_b32_e64 v3, v0, v3, s[4:5]
	v_cndmask_b32_e64 v142, 0, 1, s[4:5]
	v_mad_i64_i32 v[16:17], s[12:13], v3, s63, v[14:15]
	v_lshl_add_u64 v[16:17], v[16:17], 0, v[188:189]
	v_add_co_u32_e32 v18, vcc, s66, v16
	v_lshlrev_b64 v[0:1], 10, v[0:1]
	s_nop 0
	v_addc_co_u32_e32 v19, vcc, 0, v17, vcc
	global_load_dwordx2 v[138:139], v[18:19], off offset:3584 nt
	v_add_co_u32_e32 v16, vcc, s92, v16
	v_ashrrev_i32_e32 v3, 31, v2
	s_nop 0
	v_addc_co_u32_e32 v17, vcc, 0, v17, vcc
	global_load_dwordx2 v[50:51], v[16:17], off offset:1536 nt
	v_mad_i64_i32 v[12:13], s[4:5], v28, s63, v[14:15]
	v_lshl_add_u64 v[12:13], v[12:13], 0, v[188:189]
	v_add_co_u32_e32 v12, vcc, s92, v12
	s_nop 1
	v_addc_co_u32_e32 v13, vcc, 0, v13, vcc
	global_load_dwordx2 v[36:37], v[12:13], off offset:512 nt
	v_mad_i64_i32 v[12:13], s[4:5], v10, s63, v[14:15]
	v_lshl_add_u64 v[12:13], v[12:13], 0, v[188:189]
	v_add_co_u32_e32 v12, vcc, s92, v12
	s_nop 1
	v_addc_co_u32_e32 v13, vcc, 0, v13, vcc
; __device__ __forceinline__ float bf_lo(unsigned w) { return __uint_as_float(w << 16); }
; __device__ __forceinline__ float bf_hi(unsigned w) { return __uint_as_float(w & 0xffff0000u); }
; __device__ void conv_naive(const Params& p, int l, const bf16_t* proj, bf16_t* ycat) {
;     ...
;         for (int j = 0; j < 10; ++j) { const int ts = tb + j - 1; const bool ok = ts >= 0 && ts < SEQ; const int tc = ok ? ts : tb;
;             hh[j] = *(const u32x2*)(proj + (size_t)tc * NP + CH + c); cc[j] = *(const u32x2*)(proj + (size_t)tc * NP + CC + c);
;             if (!ok) { hh[j].x = 0u; hh[j].y = 0u; } }
; #pragma unroll
;         for (int j = 0; j < 8; ++j) bb[j] = *(const u32x2*)(proj + (size_t)(tb + j) * NP + CB + c);
;         f32x4 w[3];
; #pragma unroll
;         for (int j = 0; j < 3; ++j) w[j] = *(const f32x4*)(p.conv_w + ((size_t)l * 3 + j) * 512 + c);
;         f32x4 u[10];
; #pragma unroll
;         for (int j = 0; j < 10; ++j) { u[j][0] = bf_lo(hh[j].x) * bf_lo(cc[j].x); u[j][1] = bf_hi(hh[j].x) * bf_hi(cc[j].x); u[j][2] = bf_lo(hh[j].y) * bf_lo(cc[j].y); u[j][3] = bf_hi(hh[j].y) * bf_hi(cc[j].y); }
	global_load_dwordx2 v[26:27], v[12:13], off offset:512 nt
	v_mad_i64_i32 v[12:13], s[4:5], v8, s63, v[14:15]
	v_lshl_add_u64 v[12:13], v[12:13], 0, v[188:189]
	v_add_co_u32_e32 v12, vcc, s92, v12
	s_nop 1
	v_addc_co_u32_e32 v13, vcc, 0, v13, vcc
	global_load_dwordx2 v[22:23], v[12:13], off offset:512 nt
	v_mad_i64_i32 v[12:13], s[4:5], v6, s63, v[14:15]
	v_lshl_add_u64 v[12:13], v[12:13], 0, v[188:189]
	v_add_co_u32_e32 v12, vcc, s92, v12
	s_nop 1
	v_addc_co_u32_e32 v13, vcc, 0, v13, vcc
	global_load_dwordx2 v[20:21], v[12:13], off offset:512 nt
	v_mad_i64_i32 v[12:13], s[4:5], v4, s63, v[14:15]
	v_lshl_add_u64 v[12:13], v[12:13], 0, v[188:189]
	v_add_co_u32_e32 v12, vcc, s92, v12
	s_nop 1
	v_addc_co_u32_e32 v13, vcc, 0, v13, vcc
	global_load_dwordx2 v[18:19], v[12:13], off offset:512 nt
	v_mad_i64_i32 v[12:13], s[4:5], v2, s63, v[14:15]
	v_lshl_add_u64 v[12:13], v[12:13], 0, v[188:189]
	v_add_co_u32_e32 v12, vcc, s92, v12
	s_nop 1
	v_addc_co_u32_e32 v13, vcc, 0, v13, vcc
	global_load_dwordx2 v[16:17], v[12:13], off offset:512 nt
	v_or_b32_e32 v12, 7, v52
	v_mad_i64_i32 v[14:15], s[4:5], v12, s63, v[14:15]
	v_lshl_add_u64 v[14:15], v[14:15], 0, v[188:189]
	v_add_co_u32_e32 v14, vcc, s92, v14
	v_lshlrev_b32_e32 v52, 2, v53
	v_mov_b32_e32 v53, v189
	v_addc_co_u32_e32 v15, vcc, 0, v15, vcc
	v_lshl_add_u64 v[84:85], s[8:9], 0, v[52:53]
	global_load_dwordx2 v[14:15], v[14:15], off offset:512 nt
	s_nop 0
	global_load_dwordx4 v[76:79], v52, s[8:9]
	global_load_dwordx4 v[80:83], v52, s[8:9] offset:2048
	v_add_co_u32_e32 v52, vcc, s66, v84
	v_ashrrev_i32_e32 v13, 31, v12
	s_nop 0
	v_addc_co_u32_e32 v53, vcc, 0, v85, vcc
	global_load_dwordx4 v[84:87], v[52:53], off
	s_waitcnt vmcnt(10)
	v_cmp_ne_u32_e32 vcc, 0, v142
	s_nop 1
	v_cndmask_b32_e32 v73, 0, v139, vcc
	v_cndmask_b32_e32 v75, 0, v138, vcc
	v_cmp_ne_u32_e32 vcc, 0, v140
	s_nop 1
	v_cndmask_b32_e32 v58, 0, v120, vcc
	v_cndmask_b32_e32 v56, 0, v121, vcc
	v_cmp_ne_u32_e32 vcc, 0, v141
	s_nop 1
	v_cndmask_b32_e32 v60, 0, v122, vcc
	v_cndmask_b32_e32 v57, 0, v123, vcc
	v_cndmask_b32_e32 v62, 0, v124, vcc
	v_cndmask_b32_e32 v59, 0, v125, vcc
	v_cndmask_b32_e32 v64, 0, v126, vcc
	v_cndmask_b32_e32 v61, 0, v127, vcc
	v_cndmask_b32_e32 v66, 0, v128, vcc
	v_cndmask_b32_e32 v63, 0, v129, vcc
	v_cndmask_b32_e32 v68, 0, v130, vcc
	v_cndmask_b32_e32 v65, 0, v131, vcc
	v_cndmask_b32_e32 v67, 0, v133, vcc
	v_cndmask_b32_e32 v70, 0, v132, vcc
	v_cndmask_b32_e32 v72, 0, v134, vcc
	v_cndmask_b32_e32 v69, 0, v135, vcc
	v_cndmask_b32_e32 v71, 0, v137, vcc
	v_cndmask_b32_e32 v74, 0, v136, vcc
	v_lshlrev_b32_e32 v88, 16, v24
	v_and_b32_e32 v89, 0xffff0000, v24
	v_lshlrev_b32_e32 v24, 16, v25
	v_and_b32_e32 v25, 0xffff0000, v25
	v_lshlrev_b32_e32 v90, 16, v30
	v_and_b32_e32 v91, 0xffff0000, v30
	v_lshlrev_b32_e32 v30, 16, v31
	v_and_b32_e32 v31, 0xffff0000, v31
	v_lshlrev_b32_e32 v52, 16, v58
	v_and_b32_e32 v53, 0xffff0000, v58
	v_pk_mul_f32 v[52:53], v[88:89], v[52:53]
	v_lshlrev_b32_e32 v88, 16, v56
	v_and_b32_e32 v89, 0xffff0000, v56
	v_pk_mul_f32 v[24:25], v[24:25], v[88:89]
	v_lshlrev_b32_e32 v88, 16, v60
	v_and_b32_e32 v89, 0xffff0000, v60
	v_lshlrev_b32_e32 v56, 16, v57
	v_and_b32_e32 v57, 0xffff0000, v57
	v_pk_mul_f32 v[88:89], v[88:89], v[90:91]
	v_pk_mul_f32 v[30:31], v[56:57], v[30:31]
	v_lshlrev_b32_e32 v56, 16, v62
	v_and_b32_e32 v57, 0xffff0000, v62
	v_lshlrev_b32_e32 v90, 16, v32
	v_and_b32_e32 v91, 0xffff0000, v32
	v_lshlrev_b32_e32 v58, 16, v59
	v_and_b32_e32 v59, 0xffff0000, v59
	v_lshlrev_b32_e32 v32, 16, v33
	v_and_b32_e32 v33, 0xffff0000, v33
	v_pk_mul_f32 v[56:57], v[56:57], v[90:91]
	v_pk_mul_f32 v[32:33], v[58:59], v[32:33]
	v_lshlrev_b32_e32 v58, 16, v64
	v_and_b32_e32 v59, 0xffff0000, v64
	v_lshlrev_b32_e32 v90, 16, v34
	v_and_b32_e32 v91, 0xffff0000, v34
	v_lshlrev_b32_e32 v60, 16, v61
	v_and_b32_e32 v61, 0xffff0000, v61
	v_lshlrev_b32_e32 v34, 16, v35
	v_and_b32_e32 v35, 0xffff0000, v35
	v_pk_mul_f32 v[58:59], v[58:59], v[90:91]
	v_pk_mul_f32 v[34:35], v[60:61], v[34:35]
	v_lshlrev_b32_e32 v60, 16, v66
	v_and_b32_e32 v61, 0xffff0000, v66
	v_lshlrev_b32_e32 v90, 16, v38
	v_and_b32_e32 v91, 0xffff0000, v38
	v_lshlrev_b32_e32 v62, 16, v63
	v_and_b32_e32 v63, 0xffff0000, v63
	v_lshlrev_b32_e32 v38, 16, v39
	v_and_b32_e32 v39, 0xffff0000, v39
	v_pk_mul_f32 v[60:61], v[60:61], v[90:91]
	v_pk_mul_f32 v[38:39], v[62:63], v[38:39]
	v_lshlrev_b32_e32 v62, 16, v68
	v_and_b32_e32 v63, 0xffff0000, v68
	v_lshlrev_b32_e32 v90, 16, v40
	v_and_b32_e32 v91, 0xffff0000, v40
	v_lshlrev_b32_e32 v64, 16, v65
	v_and_b32_e32 v65, 0xffff0000, v65
	v_lshlrev_b32_e32 v40, 16, v41
	v_and_b32_e32 v41, 0xffff0000, v41
	v_pk_mul_f32 v[62:63], v[62:63], v[90:91]
	v_pk_mul_f32 v[40:41], v[64:65], v[40:41]
	v_lshlrev_b32_e32 v64, 16, v70
	v_and_b32_e32 v65, 0xffff0000, v70
	v_lshlrev_b32_e32 v90, 16, v42
	v_and_b32_e32 v91, 0xffff0000, v42
	v_lshlrev_b32_e32 v66, 16, v67
	v_and_b32_e32 v67, 0xffff0000, v67
	v_lshlrev_b32_e32 v42, 16, v43
	v_and_b32_e32 v43, 0xffff0000, v43
	v_pk_mul_f32 v[64:65], v[64:65], v[90:91]
	v_pk_mul_f32 v[42:43], v[66:67], v[42:43]
	v_lshlrev_b32_e32 v66, 16, v72
	v_and_b32_e32 v67, 0xffff0000, v72
	v_lshlrev_b32_e32 v90, 16, v46
	v_and_b32_e32 v91, 0xffff0000, v46
	v_lshlrev_b32_e32 v68, 16, v69
	v_and_b32_e32 v69, 0xffff0000, v69
	v_lshlrev_b32_e32 v46, 16, v47
	v_and_b32_e32 v47, 0xffff0000, v47
	v_pk_mul_f32 v[66:67], v[66:67], v[90:91]
	v_pk_mul_f32 v[46:47], v[68:69], v[46:47]
	v_lshlrev_b32_e32 v68, 16, v74
	v_and_b32_e32 v69, 0xffff0000, v74
	v_lshlrev_b32_e32 v90, 16, v48
	v_and_b32_e32 v91, 0xffff0000, v48
	v_lshlrev_b32_e32 v70, 16, v71
	v_and_b32_e32 v71, 0xffff0000, v71
	v_lshlrev_b32_e32 v48, 16, v49
	v_and_b32_e32 v49, 0xffff0000, v49
	v_pk_mul_f32 v[68:69], v[68:69], v[90:91]
	v_pk_mul_f32 v[48:49], v[70:71], v[48:49]
	v_lshlrev_b32_e32 v70, 16, v75
	v_and_b32_e32 v71, 0xffff0000, v75
	v_lshlrev_b32_e32 v74, 16, v50
	v_and_b32_e32 v75, 0xffff0000, v50
	s_waitcnt vmcnt(0)
; __device__ __forceinline__ unsigned cvt_pk_bf16(float lo, float hi) { unsigned r; asm("v_cvt_pk_bf16_f32 %0, %1, %2" : "=v"(r) : "v"(lo), "v"(hi)); return r; }
; __device__ __forceinline__ float bf_lo(unsigned w) { return __uint_as_float(w << 16); }
; __device__ __forceinline__ float bf_hi(unsigned w) { return __uint_as_float(w & 0xffff0000u); }
; __device__ void conv_naive(const Params& p, int l, const bf16_t* proj, bf16_t* ycat) {
;     ...
;         for (int j = 0; j < 10; ++j) { u[j][0] = bf_lo(hh[j].x) * bf_lo(cc[j].x); u[j][1] = bf_hi(hh[j].x) * bf_hi(cc[j].x); u[j][2] = bf_lo(hh[j].y) * bf_lo(cc[j].y); u[j][3] = bf_hi(hh[j].y) * bf_hi(cc[j].y); }
; #pragma unroll
;         for (int j = 0; j < 8; ++j) { const f32x4 a = w[0] * u[j] + w[1] * u[j + 1] + w[2] * u[j + 2];
;             u32x2 o; o.x = cvt_pk_bf16(a[0] * bf_lo(bb[j].x), a[1] * bf_hi(bb[j].x)); o.y = cvt_pk_bf16(a[2] * bf_lo(bb[j].y), a[3] * bf_hi(bb[j].y));
;             *(u32x2*)(ycat + (size_t)SEQ * 512 + (size_t)(tb + j) * 512 + c) = o; }
;     }
	v_pk_mul_f32 v[90:91], v[88:89], v[80:81]
	v_pk_mul_f32 v[70:71], v[70:71], v[74:75]
	v_pk_mul_f32 v[74:75], v[30:31], v[82:83]
	v_pk_fma_f32 v[52:53], v[52:53], v[76:77], v[90:91]
	v_pk_fma_f32 v[24:25], v[24:25], v[78:79], v[74:75]
	v_pk_fma_f32 v[52:53], v[56:57], v[84:85], v[52:53]
	v_lshlrev_b32_e32 v74, 16, v44
	v_and_b32_e32 v44, 0xffff0000, v44
	v_mul_f32_e32 v52, v52, v74
	v_mul_f32_e32 v44, v53, v44
	v_lshlrev_b32_e32 v72, 16, v73
	v_and_b32_e32 v73, 0xffff0000, v73
	v_lshlrev_b32_e32 v50, 16, v51
	v_and_b32_e32 v51, 0xffff0000, v51
	v_pk_fma_f32 v[24:25], v[32:33], v[86:87], v[24:25]
	v_cvt_pk_bf16_f32 v44, v52, v44
	v_lshlrev_b32_e32 v52, 16, v45
	v_and_b32_e32 v45, 0xffff0000, v45
	v_pk_mul_f32 v[50:51], v[72:73], v[50:51]
	v_lshl_add_u64 v[72:73], s[20:21], 0, v[188:189]
	v_mul_f32_e32 v24, v24, v52
	v_mul_f32_e32 v25, v25, v45
	v_cvt_pk_bf16_f32 v45, v24, v25
	v_lshl_add_u64 v[0:1], v[72:73], 0, v[0:1]
	v_pk_mul_f32 v[24:25], v[56:57], v[80:81]
	global_store_dwordx2 v[0:1], v[44:45], off nt
	v_pk_mul_f32 v[0:1], v[32:33], v[82:83]
	v_pk_fma_f32 v[24:25], v[88:89], v[76:77], v[24:25]
	v_pk_fma_f32 v[0:1], v[30:31], v[78:79], v[0:1]
	v_pk_fma_f32 v[24:25], v[58:59], v[84:85], v[24:25]
	v_lshlrev_b32_e32 v30, 16, v36
	v_mul_f32_e32 v24, v24, v30
	v_and_b32_e32 v30, 0xffff0000, v36
	v_mul_f32_e32 v25, v25, v30
	v_pk_fma_f32 v[0:1], v[34:35], v[86:87], v[0:1]
	v_cvt_pk_bf16_f32 v24, v24, v25
	v_lshlrev_b32_e32 v25, 16, v37
	v_mul_f32_e32 v0, v0, v25
	v_and_b32_e32 v25, 0xffff0000, v37
	v_mul_f32_e32 v1, v1, v25
	v_cvt_pk_bf16_f32 v25, v0, v1
	v_lshlrev_b64 v[0:1], 10, v[28:29]
	v_lshl_add_u64 v[0:1], v[72:73], 0, v[0:1]
	global_store_dwordx2 v[0:1], v[24:25], off nt
	v_pk_mul_f32 v[24:25], v[58:59], v[80:81]
	v_pk_mul_f32 v[0:1], v[34:35], v[82:83]
	v_pk_fma_f32 v[24:25], v[56:57], v[76:77], v[24:25]
	v_lshlrev_b32_e32 v28, 16, v26
	v_pk_fma_f32 v[24:25], v[60:61], v[84:85], v[24:25]
	v_and_b32_e32 v26, 0xffff0000, v26
	v_pk_fma_f32 v[0:1], v[32:33], v[78:79], v[0:1]
	v_mul_f32_e32 v24, v24, v28
	v_mul_f32_e32 v25, v25, v26
	v_pk_fma_f32 v[0:1], v[38:39], v[86:87], v[0:1]
	v_cvt_pk_bf16_f32 v24, v24, v25
	v_lshlrev_b32_e32 v25, 16, v27
	v_mul_f32_e32 v0, v0, v25
	v_and_b32_e32 v25, 0xffff0000, v27
	v_mul_f32_e32 v1, v1, v25
	v_cvt_pk_bf16_f32 v25, v0, v1
	v_lshlrev_b64 v[0:1], 10, v[10:11]
	v_pk_mul_f32 v[10:11], v[60:61], v[80:81]
	v_lshl_add_u64 v[0:1], v[72:73], 0, v[0:1]
	v_pk_fma_f32 v[10:11], v[58:59], v[76:77], v[10:11]
	global_store_dwordx2 v[0:1], v[24:25], off nt
	v_pk_mul_f32 v[0:1], v[38:39], v[82:83]
	v_pk_fma_f32 v[10:11], v[62:63], v[84:85], v[10:11]
	v_lshlrev_b32_e32 v24, 16, v22
	v_and_b32_e32 v22, 0xffff0000, v22
	v_pk_fma_f32 v[0:1], v[34:35], v[78:79], v[0:1]
	v_mul_f32_e32 v10, v10, v24
	v_mul_f32_e32 v11, v11, v22
	v_pk_fma_f32 v[0:1], v[40:41], v[86:87], v[0:1]
	v_cvt_pk_bf16_f32 v10, v10, v11
	v_lshlrev_b32_e32 v11, 16, v23
	v_mul_f32_e32 v0, v0, v11
	v_and_b32_e32 v11, 0xffff0000, v23
	v_mul_f32_e32 v1, v1, v11
	v_cvt_pk_bf16_f32 v11, v0, v1
	v_lshlrev_b64 v[0:1], 10, v[8:9]
	v_pk_mul_f32 v[8:9], v[62:63], v[80:81]
	v_lshl_add_u64 v[0:1], v[72:73], 0, v[0:1]
	v_pk_fma_f32 v[8:9], v[60:61], v[76:77], v[8:9]
	global_store_dwordx2 v[0:1], v[10:11], off nt
	v_pk_fma_f32 v[8:9], v[64:65], v[84:85], v[8:9]
	v_lshlrev_b32_e32 v10, 16, v20
	v_pk_mul_f32 v[0:1], v[40:41], v[82:83]
	v_mul_f32_e32 v8, v8, v10
	v_and_b32_e32 v10, 0xffff0000, v20
	v_pk_fma_f32 v[0:1], v[38:39], v[78:79], v[0:1]
	v_mul_f32_e32 v9, v9, v10
	v_pk_fma_f32 v[0:1], v[42:43], v[86:87], v[0:1]
	v_cvt_pk_bf16_f32 v8, v8, v9
	v_lshlrev_b32_e32 v9, 16, v21
	v_mul_f32_e32 v0, v0, v9
	v_and_b32_e32 v9, 0xffff0000, v21
	v_mul_f32_e32 v1, v1, v9
	v_cvt_pk_bf16_f32 v9, v0, v1
	v_lshlrev_b64 v[0:1], 10, v[6:7]
	v_pk_mul_f32 v[6:7], v[64:65], v[80:81]
	v_lshl_add_u64 v[0:1], v[72:73], 0, v[0:1]
	v_pk_fma_f32 v[6:7], v[62:63], v[76:77], v[6:7]
	global_store_dwordx2 v[0:1], v[8:9], off nt
	v_pk_fma_f32 v[6:7], v[66:67], v[84:85], v[6:7]
	v_lshlrev_b32_e32 v8, 16, v18
	v_pk_mul_f32 v[0:1], v[42:43], v[82:83]
	v_mul_f32_e32 v6, v6, v8
	v_and_b32_e32 v8, 0xffff0000, v18
	v_pk_fma_f32 v[0:1], v[40:41], v[78:79], v[0:1]
	v_mul_f32_e32 v7, v7, v8
	v_pk_fma_f32 v[0:1], v[46:47], v[86:87], v[0:1]
	v_cvt_pk_bf16_f32 v6, v6, v7
	v_lshlrev_b32_e32 v7, 16, v19
	v_mul_f32_e32 v0, v0, v7
	v_and_b32_e32 v7, 0xffff0000, v19
	v_mul_f32_e32 v1, v1, v7
	v_cvt_pk_bf16_f32 v7, v0, v1
	v_lshlrev_b64 v[0:1], 10, v[4:5]
	v_pk_mul_f32 v[4:5], v[66:67], v[80:81]
	v_lshl_add_u64 v[0:1], v[72:73], 0, v[0:1]
	v_pk_fma_f32 v[4:5], v[64:65], v[76:77], v[4:5]
	global_store_dwordx2 v[0:1], v[6:7], off nt
	v_pk_fma_f32 v[4:5], v[68:69], v[84:85], v[4:5]
	v_lshlrev_b32_e32 v6, 16, v16
	v_pk_mul_f32 v[0:1], v[46:47], v[82:83]
	v_mul_f32_e32 v4, v4, v6
	v_and_b32_e32 v6, 0xffff0000, v16
	v_pk_fma_f32 v[0:1], v[42:43], v[78:79], v[0:1]
	v_mul_f32_e32 v5, v5, v6
	v_pk_fma_f32 v[0:1], v[48:49], v[86:87], v[0:1]
	v_cvt_pk_bf16_f32 v4, v4, v5
	v_lshlrev_b32_e32 v5, 16, v17
	v_mul_f32_e32 v0, v0, v5
	v_and_b32_e32 v5, 0xffff0000, v17
	v_mul_f32_e32 v1, v1, v5
	v_cvt_pk_bf16_f32 v5, v0, v1
	v_lshlrev_b64 v[0:1], 10, v[2:3]
	v_pk_mul_f32 v[2:3], v[68:69], v[80:81]
	v_lshl_add_u64 v[0:1], v[72:73], 0, v[0:1]
	v_pk_fma_f32 v[2:3], v[66:67], v[76:77], v[2:3]
	global_store_dwordx2 v[0:1], v[4:5], off nt
	v_pk_fma_f32 v[2:3], v[70:71], v[84:85], v[2:3]
	v_lshlrev_b32_e32 v4, 16, v14
	v_pk_mul_f32 v[0:1], v[48:49], v[82:83]
	v_mul_f32_e32 v2, v2, v4
	v_and_b32_e32 v4, 0xffff0000, v14
	v_pk_fma_f32 v[0:1], v[46:47], v[78:79], v[0:1]
	v_mul_f32_e32 v3, v3, v4
	v_pk_fma_f32 v[0:1], v[50:51], v[86:87], v[0:1]
	v_cvt_pk_bf16_f32 v2, v2, v3
	v_lshlrev_b32_e32 v3, 16, v15
	v_mul_f32_e32 v0, v0, v3
	v_and_b32_e32 v3, 0xffff0000, v15
	v_mul_f32_e32 v1, v1, v3
	s_mov_b32 s4, 0x3ffff
	v_cvt_pk_bf16_f32 v3, v0, v1
	v_lshlrev_b64 v[0:1], 10, v[12:13]
	v_cmp_lt_i32_e32 vcc, s4, v54
	v_lshl_add_u64 v[0:1], v[72:73], 0, v[0:1]
	s_or_b64 s[10:11], vcc, s[10:11]
	global_store_dwordx2 v[0:1], v[2:3], off nt
	s_andn2_b64 exec, exec, s[10:11]
	s_cbranch_execnz .LBB0_482

;     ...
;         for (int q = 0; q < 4; ++q) { const int it = gi * 4 + q;
;             v[q][0] = (f32x4){0.f, 0.f, 0.f, 0.f}; v[q][1] = (f32x4){0.f, 0.f, 0.f, 0.f};
;             if (it < total) { const int b = it / per, r = it % per, k0 = (r / tn) * 64, n0 = (r % tn) * 64;
;                 const float* sp = src + (size_t)b * sbs + (size_t)k0 * N + n0; const int c4 = (tid & 15) * 4;
;                 if (n0 + c4 < N) { v[q][0] = *(const f32x4*)(sp + (size_t)(tid >> 4) * N + c4); v[q][1] = *(const f32x4*)(sp + (size_t)((tid >> 4) + 32) * N + c4); } } }
; __device__ void phase_convert(const Params& p, LAS unsigned char* lds) {
;     ...
;     cvt_job(tile, p.w_in, (bf16_t*)(ws + WS_WIN), NL, 1024, NIN, 1024, 0, (size_t)1024 * NIN, (size_t)NP * 1024, (int)blockIdx.x, (int)gridDim.x, 3072);
.LBB0_516:
	s_mul_hi_i32 s4, s14, 0x964fda6d
	s_add_i32 s4, s4, s14
	s_lshr_b32 s5, s4, 31
	s_ashr_i32 s17, s4, 10
	s_add_i32 s17, s17, s5
	s_mul_i32 s4, s17, 0x6d0
	s_sub_i32 s4, s14, s4
	s_mul_i32 s5, s4, 0x965
	s_lshr_b32 s6, s5, 31
	s_ashr_i32 s5, s5, 18
	s_add_i32 s5, s5, s6
	s_mul_i32 s6, s5, 0x6d
	s_sub_i32 s4, s4, s6
	s_sext_i32_i16 s4, s4
	s_lshl_b32 s4, s4, 6
	v_or_b32_e32 v0, s4, v32
	v_cmp_gt_i32_e32 vcc, s31, v0
	v_mov_b32_e32 v8, 0
	s_sext_i32_i16 s18, s5
	v_mov_b32_e32 v0, 0
	v_mov_b32_e32 v1, 0
	v_mov_b32_e32 v2, 0
	v_mov_b32_e32 v3, 0
	v_mov_b32_e32 v4, 0
	v_mov_b32_e32 v5, 0
	v_mov_b32_e32 v6, 0
	v_mov_b32_e32 v7, 0
	s_and_saveexec_b64 s[6:7], vcc
	s_cbranch_execz .LBB0_518
	v_readlane_b32 s40, v254, 48
	s_mul_i32 s8, s17, 0x1b20000
	v_readlane_b32 s42, v254, 50
	s_mul_hi_i32 s5, s17, 0x1b20000
	v_readlane_b32 s43, v254, 51
	s_add_u32 s8, s42, s8
	s_addc_u32 s5, s43, s5
	s_mul_i32 s10, s18, 0x1b2000
	s_mul_hi_i32 s9, s18, 0x1b2000
	s_add_u32 s10, s8, s10
	s_addc_u32 s11, s5, s9
	s_ashr_i32 s5, s4, 31
	s_lshl_b64 s[8:9], s[4:5], 2
	s_add_u32 s8, s10, s8
	s_addc_u32 s9, s11, s9
	v_lshl_add_u64 v[0:1], v[34:35], 2, s[8:9]
	v_lshlrev_b32_e32 v188, 2, v32
	v_lshl_add_u64 v[2:3], v[36:37], 2, s[8:9]
	v_lshl_add_u64 v[0:1], v[0:1], 0, v[188:189]
	v_lshl_add_u64 v[2:3], v[2:3], 0, v[188:189]
	global_load_dwordx4 v[4:7], v[0:1], off nt
	s_nop 0
	global_load_dwordx4 v[0:3], v[2:3], off nt
	v_readlane_b32 s41, v254, 49
	v_readlane_b32 s44, v254, 52
	v_readlane_b32 s45, v254, 53
	v_readlane_b32 s46, v254, 54
	v_readlane_b32 s47, v254, 55
	v_readlane_b32 s48, v254, 56
	v_readlane_b32 s49, v254, 57
	v_readlane_b32 s50, v254, 58
	v_readlane_b32 s51, v254, 59
	v_readlane_b32 s52, v254, 60
	v_readlane_b32 s53, v254, 61
	v_readlane_b32 s54, v254, 62
	v_readlane_b32 s55, v254, 63
.LBB0_518:
	s_or_b64 exec, exec, s[6:7]
	s_or_b32 s19, s14, 1
	s_cmpk_lt_i32 s19, 0xda0
	s_cselect_b64 s[6:7], -1, 0
	s_cmpk_gt_i32 s19, 0xd9f
	s_mul_hi_i32 s20, s19, 0x964fda6d
	v_mov_b32_e32 v9, 0
	v_mov_b32_e32 v10, 0
	v_mov_b32_e32 v11, 0
	v_mov_b32_e32 v12, 0
	v_mov_b32_e32 v13, 0
	v_mov_b32_e32 v14, 0
	v_mov_b32_e32 v15, 0
	s_cbranch_scc1 .LBB0_522
	s_add_i32 s5, s20, s19
	s_lshr_b32 s8, s5, 31
	s_ashr_i32 s5, s5, 10
	s_add_i32 s5, s5, s8
	s_mul_i32 s8, s5, 0x6d0
	s_sub_i32 s8, s19, s8
	s_sext_i32_i16 s9, s8
	s_mulk_i32 s9, 0x965
	s_lshr_b32 s10, s9, 31
	s_ashr_i32 s11, s9, 18
	s_add_i32 s11, s11, s10
	s_mul_i32 s9, s11, 0x6d
	s_sub_i32 s8, s8, s9
	s_sext_i32_i16 s8, s8
	s_lshl_b32 s10, s8, 6
	v_or_b32_e32 v8, s10, v32
	v_cmp_gt_i32_e32 vcc, s31, v8
	v_mov_b32_e32 v15, 0
	v_mov_b32_e32 v14, 0
	v_mov_b32_e32 v13, 0
	v_mov_b32_e32 v12, 0
	v_mov_b32_e32 v11, 0
	v_mov_b32_e32 v10, 0
	v_mov_b32_e32 v9, 0
	v_mov_b32_e32 v8, 0
	s_and_saveexec_b64 s[8:9], vcc
	s_cbranch_execz .LBB0_521
	v_readlane_b32 s40, v254, 48
	s_mul_hi_i32 s12, s5, 0x1b20000
	s_mul_i32 s5, s5, 0x1b20000
	v_readlane_b32 s42, v254, 50
	v_readlane_b32 s43, v254, 51
	s_add_u32 s5, s42, s5
	s_sext_i32_i16 s11, s11
	s_addc_u32 s12, s43, s12
	s_mul_hi_i32 s13, s11, 0x1b2000
	s_mul_i32 s11, s11, 0x1b2000
	s_add_u32 s5, s5, s11
	s_addc_u32 s12, s12, s13
	s_ashr_i32 s11, s10, 31
	s_lshl_b64 s[10:11], s[10:11], 2
	s_add_u32 s10, s5, s10
	s_addc_u32 s11, s12, s11
	v_lshl_add_u64 v[8:9], v[34:35], 2, s[10:11]
	v_lshlrev_b32_e32 v188, 2, v32
	v_lshl_add_u64 v[10:11], v[36:37], 2, s[10:11]
	v_lshl_add_u64 v[8:9], v[8:9], 0, v[188:189]
	v_lshl_add_u64 v[10:11], v[10:11], 0, v[188:189]
	global_load_dwordx4 v[12:15], v[8:9], off nt
	s_nop 0
	global_load_dwordx4 v[8:11], v[10:11], off nt
	v_readlane_b32 s41, v254, 49
	v_readlane_b32 s44, v254, 52
	v_readlane_b32 s45, v254, 53
	v_readlane_b32 s46, v254, 54
	v_readlane_b32 s47, v254, 55
	v_readlane_b32 s48, v254, 56
	v_readlane_b32 s49, v254, 57
	v_readlane_b32 s50, v254, 58
	v_readlane_b32 s51, v254, 59
	v_readlane_b32 s52, v254, 60
	v_readlane_b32 s53, v254, 61
	v_readlane_b32 s54, v254, 62
	v_readlane_b32 s55, v254, 63

;     ...
;         for (int q = 0; q < 4; ++q) { const int it = gi * 4 + q;
;             v[q][0] = (f32x4){0.f, 0.f, 0.f, 0.f}; v[q][1] = (f32x4){0.f, 0.f, 0.f, 0.f};
;             if (it < total) { const int b = it / per, r = it % per, k0 = (r / tn) * 64, n0 = (r % tn) * 64;
;                 const float* sp = src + (size_t)b * sbs + (size_t)k0 * N + n0; const int c4 = (tid & 15) * 4;
;                 if (n0 + c4 < N) { v[q][0] = *(const f32x4*)(sp + (size_t)(tid >> 4) * N + c4); v[q][1] = *(const f32x4*)(sp + (size_t)((tid >> 4) + 32) * N + c4); } } }
; __device__ void phase_convert(const Params& p, LAS unsigned char* lds) {
;     ...
;     cvt_job(tile, p.w_in, (bf16_t*)(ws + WS_WIN), NL, 1024, NIN, 1024, 0, (size_t)1024 * NIN, (size_t)NP * 1024, (int)blockIdx.x, (int)gridDim.x, 3072);
.LBB0_522:
	s_or_b32 s21, s14, 2
	s_cmpk_lt_i32 s21, 0xda0
	v_mov_b32_e32 v16, 0
	s_cselect_b64 s[8:9], -1, 0
	s_cmpk_gt_i32 s21, 0xd9f
	s_mul_hi_i32 s22, s21, 0x964fda6d
	v_mov_b32_e32 v20, 0
	v_mov_b32_e32 v21, 0
	v_mov_b32_e32 v22, 0
	v_mov_b32_e32 v23, 0
	v_mov_b32_e32 v24, 0
	v_mov_b32_e32 v25, 0
	v_mov_b32_e32 v26, 0
	v_mov_b32_e32 v27, 0
	s_cbranch_scc1 .LBB0_526
	s_add_i32 s5, s22, s21
	s_lshr_b32 s10, s5, 31
	s_ashr_i32 s5, s5, 10
	s_add_i32 s5, s5, s10
	s_mul_i32 s10, s5, 0x6d0
	s_sub_i32 s10, s21, s10
	s_sext_i32_i16 s11, s10
	s_mulk_i32 s11, 0x965
	s_lshr_b32 s12, s11, 31
	s_ashr_i32 s13, s11, 18
	s_add_i32 s13, s13, s12
	s_mul_i32 s11, s13, 0x6d
	s_sub_i32 s10, s10, s11
	s_sext_i32_i16 s10, s10
	s_lshl_b32 s12, s10, 6
	v_or_b32_e32 v17, s12, v32
	v_cmp_gt_i32_e32 vcc, s31, v17
	v_mov_b32_e32 v27, 0
	v_mov_b32_e32 v26, 0
	v_mov_b32_e32 v25, 0
	v_mov_b32_e32 v24, 0
	v_mov_b32_e32 v23, 0
	v_mov_b32_e32 v22, 0
	v_mov_b32_e32 v21, 0
	v_mov_b32_e32 v20, 0
	s_and_saveexec_b64 s[10:11], vcc
	s_cbranch_execz .LBB0_525
	v_readlane_b32 s40, v254, 48
	s_mul_hi_i32 s15, s5, 0x1b20000
	s_mul_i32 s5, s5, 0x1b20000
	v_readlane_b32 s42, v254, 50
	v_readlane_b32 s43, v254, 51
	s_add_u32 s5, s42, s5
	s_sext_i32_i16 s13, s13
	s_addc_u32 s15, s43, s15
	s_mul_hi_i32 s23, s13, 0x1b2000
	s_mul_i32 s13, s13, 0x1b2000
	s_add_u32 s5, s5, s13
	s_addc_u32 s15, s15, s23
	s_ashr_i32 s13, s12, 31
	s_lshl_b64 s[12:13], s[12:13], 2
	s_add_u32 s12, s5, s12
	s_addc_u32 s13, s15, s13
	v_lshl_add_u64 v[18:19], v[34:35], 2, s[12:13]
	v_lshlrev_b32_e32 v188, 2, v32
	v_lshl_add_u64 v[20:21], v[36:37], 2, s[12:13]
	v_lshl_add_u64 v[18:19], v[18:19], 0, v[188:189]
	v_lshl_add_u64 v[20:21], v[20:21], 0, v[188:189]
	global_load_dwordx4 v[24:27], v[18:19], off nt
	s_nop 0
	global_load_dwordx4 v[20:23], v[20:21], off nt
	v_readlane_b32 s41, v254, 49
	v_readlane_b32 s44, v254, 52
	v_readlane_b32 s45, v254, 53
	v_readlane_b32 s46, v254, 54
	v_readlane_b32 s47, v254, 55
	v_readlane_b32 s48, v254, 56
	v_readlane_b32 s49, v254, 57
	v_readlane_b32 s50, v254, 58
	v_readlane_b32 s51, v254, 59
	v_readlane_b32 s52, v254, 60
	v_readlane_b32 s53, v254, 61
	v_readlane_b32 s54, v254, 62
	v_readlane_b32 s55, v254, 63

;     ...
;         for (int q = 0; q < 4; ++q) { const int it = gi * 4 + q;
;             v[q][0] = (f32x4){0.f, 0.f, 0.f, 0.f}; v[q][1] = (f32x4){0.f, 0.f, 0.f, 0.f};
;             if (it < total) { const int b = it / per, r = it % per, k0 = (r / tn) * 64, n0 = (r % tn) * 64;
;                 const float* sp = src + (size_t)b * sbs + (size_t)k0 * N + n0; const int c4 = (tid & 15) * 4;
;                 if (n0 + c4 < N) { v[q][0] = *(const f32x4*)(sp + (size_t)(tid >> 4) * N + c4); v[q][1] = *(const f32x4*)(sp + (size_t)((tid >> 4) + 32) * N + c4); } } }
; __device__ void phase_convert(const Params& p, LAS unsigned char* lds) {
;     ...
;     cvt_job(tile, p.w_in, (bf16_t*)(ws + WS_WIN), NL, 1024, NIN, 1024, 0, (size_t)1024 * NIN, (size_t)NP * 1024, (int)blockIdx.x, (int)gridDim.x, 3072);
.LBB0_526:
	s_or_b32 s23, s14, 3
	s_cmpk_lt_i32 s23, 0xda0
	s_cselect_b64 s[10:11], -1, 0
	s_cmpk_gt_i32 s23, 0xd9f
	s_mul_hi_i32 s24, s23, 0x964fda6d
	v_mov_b32_e32 v17, 0
	v_mov_b32_e32 v18, 0
	v_mov_b32_e32 v19, 0
	v_mov_b32_e32 v28, 0
	v_mov_b32_e32 v29, 0
	v_mov_b32_e32 v30, 0
	v_mov_b32_e32 v31, 0
	s_cbranch_scc1 .LBB0_530
	s_add_i32 s5, s24, s23
	s_lshr_b32 s12, s5, 31
	s_ashr_i32 s5, s5, 10
	s_add_i32 s5, s5, s12
	s_mul_i32 s12, s5, 0x6d0
	s_sub_i32 s12, s23, s12
	s_sext_i32_i16 s13, s12
	s_mulk_i32 s13, 0x965
	s_lshr_b32 s14, s13, 31
	s_ashr_i32 s15, s13, 18
	s_add_i32 s15, s15, s14
	s_mul_i32 s13, s15, 0x6d
	s_sub_i32 s12, s12, s13
	s_sext_i32_i16 s12, s12
	s_lshl_b32 s14, s12, 6
	v_or_b32_e32 v16, s14, v32
	v_cmp_gt_i32_e32 vcc, s31, v16
	v_mov_b32_e32 v31, 0
	v_mov_b32_e32 v30, 0
	v_mov_b32_e32 v29, 0
	v_mov_b32_e32 v28, 0
	v_mov_b32_e32 v19, 0
	v_mov_b32_e32 v18, 0
	v_mov_b32_e32 v17, 0
	v_mov_b32_e32 v16, 0
	s_and_saveexec_b64 s[12:13], vcc
	s_cbranch_execz .LBB0_529
	v_readlane_b32 s40, v254, 48
	s_mul_hi_i32 s25, s5, 0x1b20000
	s_mul_i32 s5, s5, 0x1b20000
	v_readlane_b32 s42, v254, 50
	v_readlane_b32 s43, v254, 51
	s_add_u32 s5, s42, s5
	s_sext_i32_i16 s15, s15
	s_addc_u32 s25, s43, s25
	s_mul_hi_i32 s26, s15, 0x1b2000
	s_mul_i32 s15, s15, 0x1b2000
	s_add_u32 s5, s5, s15
	s_addc_u32 s25, s25, s26
	s_ashr_i32 s15, s14, 31
	s_lshl_b64 s[14:15], s[14:15], 2
	s_add_u32 s14, s5, s14
	s_addc_u32 s15, s25, s15
	v_lshl_add_u64 v[16:17], v[34:35], 2, s[14:15]
	v_lshlrev_b32_e32 v188, 2, v32
	v_lshl_add_u64 v[18:19], v[36:37], 2, s[14:15]
	v_lshl_add_u64 v[16:17], v[16:17], 0, v[188:189]
	v_lshl_add_u64 v[18:19], v[18:19], 0, v[188:189]
	global_load_dwordx4 v[28:31], v[16:17], off nt
	s_nop 0
	global_load_dwordx4 v[16:19], v[18:19], off nt
	v_readlane_b32 s41, v254, 49
	v_readlane_b32 s44, v254, 52
	v_readlane_b32 s45, v254, 53
	v_readlane_b32 s46, v254, 54
	v_readlane_b32 s47, v254, 55
	v_readlane_b32 s48, v254, 56
	v_readlane_b32 s49, v254, 57
	v_readlane_b32 s50, v254, 58
	v_readlane_b32 s51, v254, 59
	v_readlane_b32 s52, v254, 60
	v_readlane_b32 s53, v254, 61
	v_readlane_b32 s54, v254, 62
	v_readlane_b32 s55, v254, 63

; __device__ __forceinline__ unsigned cvt_pk_bf16(float lo, float hi) { unsigned r; asm("v_cvt_pk_bf16_f32 %0, %1, %2" : "=v"(r) : "v"(lo), "v"(hi)); return r; }
; __device__ __forceinline__ int fresh_tid() { int t = threadIdx.x; asm volatile("" : "+v"(t)); return t; }
; __device__ void phase_convert(const Params& p, LAS unsigned char* lds) {
;     ...
;     const f32x4* x4 = (const f32x4*)p.x; u32x2* xb = (u32x2*)(ws + WS_XB);
;     { const size_t stride = (size_t)gridDim.x * NTHREADS;
;       size_t i = (size_t)blockIdx.x * NTHREADS + fresh_tid();
;       for (; i + 3 * stride < (size_t)SEQ * DM / 4; i += 4 * stride) {
;         f32x4 v[4];
; #pragma unroll
;         for (int q = 0; q < 4; ++q) v[q] = x4[i + q * stride];
; #pragma unroll
;         for (int q = 0; q < 4; ++q) { u32x2 w; w.x = cvt_pk_bf16(v[q][0], v[q][1]); w.y = cvt_pk_bf16(v[q][2], v[q][3]); xb[i + q * stride] = w; } }
.LBB0_762:
	v_lshl_add_u64 v[10:11], v[2:3], 0, s[10:11]
	v_lshl_add_u64 v[14:15], v[2:3], 0, s[16:17]
	v_lshl_add_u64 v[18:19], v[2:3], 0, s[20:21]
	global_load_dwordx4 v[6:9], v[2:3], off nt
	s_nop 0
	global_load_dwordx4 v[10:13], v[10:11], off nt
	s_nop 0
	global_load_dwordx4 v[14:17], v[14:15], off nt
	s_nop 0
	global_load_dwordx4 v[18:21], v[18:19], off nt
	v_lshl_add_u64 v[0:1], v[0:1], 0, s[8:9]
	v_lshl_add_u64 v[28:29], s[18:19], 0, v[0:1]
	v_readlane_b32 s16, v255, 4
	v_cmp_lt_u64_e32 vcc, s[24:25], v[28:29]
	v_readlane_b32 s17, v255, 5
	s_waitcnt vmcnt(0)
	v_cvt_pk_bf16_f32 v6, v6, v7
	v_cvt_pk_bf16_f32 v7, v8, v9
	v_lshl_add_u64 v[22:23], v[4:5], 0, s[12:13]
	v_lshl_add_u64 v[24:25], v[4:5], 0, s[10:11]
	v_lshl_add_u64 v[26:27], v[4:5], 0, s[22:23]
	v_lshl_add_u64 v[2:3], v[2:3], 0, s[14:15]
	s_or_b64 s[6:7], vcc, s[6:7]
	global_store_dwordx2 v[4:5], v[6:7], off
	v_lshl_add_u64 v[4:5], v[4:5], 0, s[16:17]
	v_cvt_pk_bf16_f32 v6, v10, v11
	v_cvt_pk_bf16_f32 v7, v12, v13
	v_cvt_pk_bf16_f32 v8, v14, v15
	v_cvt_pk_bf16_f32 v9, v16, v17
	v_cvt_pk_bf16_f32 v10, v18, v19
	v_cvt_pk_bf16_f32 v11, v20, v21
	global_store_dwordx2 v[22:23], v[6:7], off
	global_store_dwordx2 v[24:25], v[8:9], off
	global_store_dwordx2 v[26:27], v[10:11], off
	s_andn2_b64 exec, exec, s[6:7]
	s_cbranch_execnz .LBB0_762
	s_or_b64 exec, exec, s[6:7]

; __device__ __forceinline__ unsigned cvt_pk_bf16(float lo, float hi) { unsigned r; asm("v_cvt_pk_bf16_f32 %0, %1, %2" : "=v"(r) : "v"(lo), "v"(hi)); return r; }
; __device__ void phase_convert(const Params& p, LAS unsigned char* lds) {
;     ...
;       for (; i < (size_t)SEQ * DM / 4; i += stride) { const f32x4 v = x4[i]; u32x2 w; w.x = cvt_pk_bf16(v[0], v[1]); w.y = cvt_pk_bf16(v[2], v[3]); xb[i] = w; } }
.LBB0_766:
	v_lshl_add_u64 v[0:1], v[0:1], 0, s[8:9]
	global_load_dwordx4 v[6:9], v[2:3], off nt
	v_cmp_lt_u64_e32 vcc, s[14:15], v[0:1]
	v_lshl_add_u64 v[2:3], v[2:3], 0, s[10:11]
	s_or_b64 s[6:7], vcc, s[6:7]
	s_waitcnt vmcnt(0)
	v_cvt_pk_bf16_f32 v6, v6, v7
	v_cvt_pk_bf16_f32 v7, v8, v9
	global_store_dwordx2 v[4:5], v[6:7], off
	v_lshl_add_u64 v[4:5], v[4:5], 0, s[12:13]
	s_andn2_b64 exec, exec, s[6:7]
	s_cbranch_execnz .LBB0_766
	s_getpc_b64 s[98:99]
